# MLA item order: every workgroup of an XCD streams a different (batch, head), pair = XCD + 8*round (no K/V sharing through L2, no same-line contention)
# speedup vs baseline: 1.0007x; 1.0007x over previous
; template <bool MLA> __device__ __forceinline__ void attn_unit(const AttnP& P, int b, int hh, int qb, LAS char* lds) {
;     ...
;     const int qlo = q0 + wid * 32, qm = qlo + r32 - 4 * hi;
;     bf16x8 qr[NQF];
;     const size_t qrow = rowbase + qlo + r32;
;     if constexpr (MLA) {
; #pragma unroll
;         for (int d0 = 0; d0 < 8; ++d0) qr[d0] = *(const bf16x8*)(P.QN + qrow * 2048 + hh * 128 + d0 * 16 + hi * 8);
; #pragma unroll
;         for (int d0 = 0; d0 < 4; ++d0) qr[8 + d0] = *(const bf16x8*)(P.QR + qrow * 1024 + hh * 64 + d0 * 16 + hi * 8);
;     } else {
; #pragma unroll
;         for (int d0 = 0; d0 < 4; ++d0) qr[d0] = *(const bf16x8*)(P.QS + qrow * 2048 + hh * 64 + d0 * 16 + hi * 8);
;         if (tid < 128) bias_l[tid] = P.rel[(int)T5B[tid] * 32 + hh] * (1.0f / SCALE);
;     }
;     bf16x8 sk0, sv0;
;     const int sr8 = tid >> 3, ch8 = tid & 7;
;     const bf16_t* Kg; const bf16_t* Vg; const bf16_t* Rg = nullptr;
;     unsigned okA = 0, okB = 0, orp = 0, ovA = 0, ovB = 0;
;     if constexpr (MLA) {
;         Kg = P.KN + rowbase * 2048 + hh * 128; Vg = P.V + rowbase * 2048 + hh * 128; Rg = P.KR + rowbase * 64;
;         { const int rA = 4 * wid + (lane >> 4), rB = rA + 32, cp = lane & 15; okA = (unsigned)(rA * 2048 + ((cp ^ (rA & 7)) << 3)); okB = (unsigned)(rB * 2048 + ((cp ^ (rB & 7)) << 3)); }
;         { const int rr = 8 * wid + (lane >> 3), cp = lane & 7; orp = (unsigned)(rr * 64 + ((cp ^ (rr & 7)) << 3)); }
;         { const int stA = 2 * wid + (lane >> 5), stB = stA + 16; const int kl = (lane & 31) >> 2, c8 = 8 * (lane & 3);
;           const int kkA = (stA >> 2) * 8 + kl, kkB = (stB >> 2) * 8 + kl;
;           const int kA = (kkA & ~0xC) | ((kkA & 4) << 1) | ((kkA & 8) >> 1), kB = (kkB & ~0xC) | ((kkB & 4) << 1) | ((kkB & 8) >> 1);
;           ovA = (unsigned)(kA * 2048 + 32 * (stA & 3) + c8); ovB = (unsigned)(kB * 2048 + 32 * (stB & 3) + c8); }
;     } else { Kg = P.KS + (rowbase + sr8) * 256 + (hh >> 3) * 64 + ch8 * 8; Vg = P.VS + (rowbase + sr8) * 256 + (hh >> 3) * 64 + ch8 * 8; }
;     const int kws = KSWZ64(sr8, ch8), vst0 = v_st<NCB>(sr8, ch8 * 8);
;     ...
;     float m_reg = MLA ? 0.f : P.sinks[hh] * (1.0f / SCALE), l_reg = MLA ? 0.f : 1.f;
;     f32x16 o[NCB];
; #pragma unroll
;     for (int d = 0; d < NCB; ++d) o[d] = f32x16{};
;     const int vb0 = (int)(uintptr_t)V_lds + v_rd_base(lane);
.Lm16_unit:
	s_and_b32 s33, s28, 7
	s_lshr_b32 s37, s28, 8
	s_lshl_b32 s37, s37, 3
	s_or_b32 s33, s33, s37
	s_cmp_eq_u32 s29, 0
	s_cbranch_scc0 .Lm16_qb_ok
	s_sub_u32 s33, 63, s33
.Lm16_qb_ok:
	s_bfe_u32 s36, s28, 0x50003
	s_and_b32 s63, s36, 15
	s_lshr_b32 s64, s36, 4
	s_lshl_b32 s40, s33, 2
	s_add_u32 s40, s40, 4
	s_lshl_b32 s43, s33, 8
	s_lshl_b32 s36, s4, 5
	s_add_u32 s43, s43, s36
	s_lshl_b32 s36, s64, 14
	s_add_u32 s36, s36, s43
	s_lshl_b32 s37, s36, 12
	s_lshl_b32 s59, s63, 8
	s_add_u32 s37, s37, s59
	s_add_u32 s66, s6, s37
	s_addc_u32 s67, s7, 0
	s_lshl_b32 s37, s36, 11
	s_lshl_b32 s59, s63, 7
	s_add_u32 s37, s37, s59
	s_add_u32 s68, s8, s37
	s_addc_u32 s69, s9, 0
	s_lshl_b32 s37, s64, 26
	s_lshl_b32 s59, s63, 8
	s_add_u32 s37, s37, s59
	s_add_u32 s46, s12, s37
	s_addc_u32 s47, s13, 0
	s_add_u32 s48, s16, s37
	s_addc_u32 s49, s17, 0
	s_lshl_b32 s37, s64, 21
	s_add_u32 s50, s14, s37
	s_addc_u32 s51, s15, 0
	global_load_dwordx4 v[66:69], v237, s[66:67] offset:0
	global_load_dwordx4 v[70:73], v237, s[66:67] offset:64
	global_load_dwordx4 v[74:77], v237, s[66:67] offset:128
	global_load_dwordx4 v[78:81], v237, s[66:67] offset:192
	global_load_dwordx4 v[82:85], v239, s[68:69] offset:0
	global_load_dwordx4 v[86:89], v239, s[68:69] offset:64
	global_load_dwordx4 v[90:93], v238, s[66:67] offset:0
	global_load_dwordx4 v[94:97], v238, s[66:67] offset:64
	global_load_dwordx4 v[98:101], v238, s[66:67] offset:128
	global_load_dwordx4 v[102:105], v238, s[66:67] offset:192
	global_load_dwordx4 v[106:109], v240, s[68:69] offset:0
	global_load_dwordx4 v[110:113], v240, s[68:69] offset:64
	s_mov_b32 s70, 0x8000
	s_mov_b32 s71, 0
	s_add_i32 s36, s5, s70
	s_mov_b32 m0, s36
	s_nop 0
	global_load_lds_dwordx4 v232, s[46:47]
	s_add_i32 m0, s36, 0x2000
	s_nop 0
	global_load_lds_dwordx4 v233, s[46:47]
	s_add_i32 m0, s36, 0x4000
	s_nop 0
	global_load_lds_dwordx4 v234, s[50:51]
	s_add_i32 s36, s5, s71
	s_mov_b32 m0, s36
	s_nop 0
	global_load_lds_dwordx4 v235, s[48:49]
	s_add_i32 m0, s36, 0x2000
	s_nop 0
	global_load_lds_dwordx4 v236, s[48:49]
	s_add_u32 s46, s46, 0x40000
	s_addc_u32 s47, s47, 0
	s_add_u32 s48, s48, 0x40000
	s_addc_u32 s49, s49, 0
	s_add_u32 s50, s50, 0x2000
	s_addc_u32 s51, s51, 0
	v_mov_b32_e32 v2, 0
	v_mov_b32_e32 v3, 0
	v_mov_b32_e32 v4, 0
	v_mov_b32_e32 v5, 0
	v_mov_b32_e32 v6, 0
	v_mov_b32_e32 v7, 0
	v_mov_b32_e32 v8, 0
	v_mov_b32_e32 v9, 0
	v_mov_b32_e32 v10, 0
	v_mov_b32_e32 v11, 0
	v_mov_b32_e32 v12, 0
	v_mov_b32_e32 v13, 0
	v_mov_b32_e32 v14, 0
	v_mov_b32_e32 v15, 0
	v_mov_b32_e32 v16, 0
	v_mov_b32_e32 v17, 0
	v_mov_b32_e32 v18, 0
	v_mov_b32_e32 v19, 0
	v_mov_b32_e32 v20, 0
	v_mov_b32_e32 v21, 0
	v_mov_b32_e32 v22, 0
	v_mov_b32_e32 v23, 0
	v_mov_b32_e32 v24, 0
	v_mov_b32_e32 v25, 0
	v_mov_b32_e32 v26, 0
	v_mov_b32_e32 v27, 0
	v_mov_b32_e32 v28, 0
	v_mov_b32_e32 v29, 0
	v_mov_b32_e32 v30, 0
	v_mov_b32_e32 v31, 0
	v_mov_b32_e32 v32, 0
	v_mov_b32_e32 v33, 0
	v_mov_b32_e32 v34, 0
	v_mov_b32_e32 v35, 0
	v_mov_b32_e32 v36, 0
	v_mov_b32_e32 v37, 0
	v_mov_b32_e32 v38, 0
	v_mov_b32_e32 v39, 0
	v_mov_b32_e32 v40, 0
	v_mov_b32_e32 v41, 0
	v_mov_b32_e32 v42, 0
	v_mov_b32_e32 v43, 0
	v_mov_b32_e32 v44, 0
	v_mov_b32_e32 v45, 0
	v_mov_b32_e32 v46, 0
	v_mov_b32_e32 v47, 0
	v_mov_b32_e32 v48, 0
	v_mov_b32_e32 v49, 0
	v_mov_b32_e32 v50, 0
	v_mov_b32_e32 v51, 0
	v_mov_b32_e32 v52, 0
	v_mov_b32_e32 v53, 0
	v_mov_b32_e32 v54, 0
	v_mov_b32_e32 v55, 0
	v_mov_b32_e32 v56, 0
	v_mov_b32_e32 v57, 0
	v_mov_b32_e32 v58, 0
	v_mov_b32_e32 v59, 0
	v_mov_b32_e32 v60, 0
	v_mov_b32_e32 v61, 0
	v_mov_b32_e32 v62, 0
	v_mov_b32_e32 v63, 0
	v_mov_b32_e32 v64, 0
	v_mov_b32_e32 v65, 0
	v_mov_b32_e32 v218, 0
	v_mov_b32_e32 v146, 0
	v_mov_b32_e32 v154, 0x3f803f80
	v_mov_b32_e32 v147, 0
	v_mov_b32_e32 v155, 0x3f803f80
	v_mov_b32_e32 v148, 0
	v_mov_b32_e32 v156, 0x3f803f80
	v_mov_b32_e32 v149, 0
	v_mov_b32_e32 v157, 0x3f803f80
	v_mov_b32_e32 v208, 0xc0e00000
	v_mov_b32_e32 v209, 0xc0e00000
	v_mov_b32_e32 v210, 0xc0e00000
	v_mov_b32_e32 v211, 0xc0e00000
	v_mov_b32_e32 v219, 0
	v_mov_b32_e32 v150, 0
	v_mov_b32_e32 v154, 0x3f803f80
	v_mov_b32_e32 v151, 0
	v_mov_b32_e32 v155, 0x3f803f80
	v_mov_b32_e32 v152, 0
	v_mov_b32_e32 v156, 0x3f803f80
	v_mov_b32_e32 v153, 0
	v_mov_b32_e32 v157, 0x3f803f80
	v_mov_b32_e32 v212, 0xc0e00000
	v_mov_b32_e32 v213, 0xc0e00000
	v_mov_b32_e32 v214, 0xc0e00000
	v_mov_b32_e32 v215, 0xc0e00000
	s_mov_b32 s41, 0
	s_mov_b32 s42, 0
	s_waitcnt vmcnt(0)
	s_barrier
